# v50 + P5 work shift: last 8192 down2 tiles converted by the 64 WGs idle in P8 partial last round (private copy of P0 static loop), P5 deferred queue 128 big batches shorter
# speedup vs baseline: 1.0137x; 1.0061x over previous
; __global__ void __launch_bounds__(NWAVES * 64, 2) fwd(Args args) {
;     ...
;           for (;;) {
;             __syncthreads();
;             if (tid == 0) MISC[16] = qpre;
;             __syncthreads();
;             constexpr int NB64 = (NCB * 3) / 4, NB16 = (NCB - NB64) * 4;
;             const unsigned q = MISC[16]; if (q >= 512u + (DEFER_AT == 5 ? (unsigned)(NB64 + NB16) : 0u)) break;
.LBB0_643:
	s_or_b64 exec, exec, s[2:3]
	s_waitcnt lgkmcnt(0)
	s_barrier
	ds_read_b32 v0, v164
	s_movk_i32 s2, 0x576
	s_waitcnt lgkmcnt(0)
	v_cmp_lt_u32_e64 s[2:3], s2, v0
	v_readfirstlane_b32 s25, v0
	s_and_b64 vcc, exec, s[2:3]
	s_cbranch_vccnz .LBB0_640
	s_and_saveexec_b64 s[6:7], s[4:5]
	s_cbranch_execz .LBB0_646
	v_mov_b32_e32 v0, v161
	s_nop 0
	v_ashrrev_i32_e32 v1, 31, v0
	v_lshl_add_u64 v[0:1], v[0:1], 2, s[44:45]
	global_atomic_add v162, v[0:1], v165, off sc0

; #define REFRESH_IDS() do { lane = fresh_lane(); tid = wave * 64 + lane; } while (0)
; __global__ void __launch_bounds__(NWAVES * 64, 2) fwd(Args args) {
;     ...
;             const unsigned q = MISC[16]; if (q >= 512u + (DEFER_AT == 5 ? (unsigned)(NB64 + NB16) : 0u)) break;
;             if (tid == 0) { int z = 0; asm volatile("" : "+v"(z)); qpre = __hip_atomic_fetch_add(ctl + CW_AQ + z, 1u, __ATOMIC_RELAXED, __HIP_MEMORY_SCOPE_AGENT); }
;             REFRESH_IDS();
;     ...
;             const bool conv = DEFER_AT == 5 ? (q < 1024u ? (q & 1u) != 0u : true) : false; const int idx = DEFER_AT == 5 ? (q < 1024u ? (int)(q >> 1) : (int)(q - 512u)) : (int)q;
;     ...
;             const bool conv = q >= 512u; const int idx = conv ? (int)(q - 512u) : (int)q;
;     ...
;             const bool conv = q < (unsigned)NCB; const int idx = conv ? (int)q : (int)(q - (unsigned)NCB);
;     ...
;             if (!conv) attn_wg(PROJ, CONCAT, idx, L, tid, lane, wave);
;             else {
;                 const bool small = idx >= NB64; const int first = NI0 + (small ? NB64 * 64 + (idx - NB64) * 16 : idx * 64) + wave;
.LBB0_679:
	s_and_b64 vcc, exec, s[4:5]
	s_cbranch_vccz .LBB0_640
	s_add_i32 s4, s25, 0xfffffe00
	s_lshl_b32 s58, s4, 4
	s_addk_i32 s58, 0x3990
	s_lshl_b32 s42, s4, 6
	s_cmpk_gt_u32 s4, 0x132
	s_cselect_b32 s5, s58, s42
	s_add_i32 s25, s86, s5
	s_cmpk_lt_u32 s4, 0x133
	s_mov_b64 s[4:5], -1
	s_cbranch_scc0 .LBB0_882
	s_add_i32 s42, s42, s28
	s_cmpk_gt_u32 s42, 0xfff
	s_cbranch_scc0 .LBB0_685
	s_cmpk_gt_u32 s42, 0x65ff
	s_cbranch_scc0 .LBB0_942
	s_and_b32 s4, s42, 0x7ffffc0
	s_add_i32 s64, s4, 0xffff9a00
	s_mov_b64 s[70:71], 0
	s_cbranch_execz .LBB0_943

; #define LAS __attribute__((address_space(3)))
; #define REFRESH_IDS() do { lane = fresh_lane(); tid = wave * 64 + lane; } while (0)
; #define GRID_BAR() xcd_barrier(bar)
; #define GRID_BAR() do { } while (0)
; #define BOTH(k) (IN(k) && IN((k) + 1))
; __global__ void __launch_bounds__(NWAVES * 64, 2) fwd(Args args) {
;     ...
;     if (IN(0)) {
;         REFRESH_IDS();
;         LAS float* scr = (LAS float*)(L + wave * (64 * 65 * 4));
;         const int NS0 = ((NI0 / 32 * 27) / NGW) * NGW;
;         P0_RUN(gw, NS0, NGW);
;     ...
;     if (IN(8)) {
;         REFRESH_IDS();
;         pg8::Gemm g{XB, Wgu2, M, 2 * FF, D, LDD, LDD}; pg8::StaticOrder S; S.init(M, 2 * FF, G, bx);
;         pg8::EpiGateUp E{ACT, ssq + 2 * M};
;         pg8::gemm_phase<pg8::EpiGateUp, pg8::StaticOrder, true, true>(L, g, S, E, wave);
;         if (BOTH(8)) GRID_BAR();
.LBB0_1140:
	s_cmpk_lt_u32 s8, 0xc0
	s_cbranch_scc1 .Lhb_done
	v_writelane_b32 v238, s0, 0
	v_writelane_b32 v238, s1, 1
	v_writelane_b32 v238, s2, 2
	v_writelane_b32 v238, s3, 3
	v_writelane_b32 v238, s4, 4
	v_writelane_b32 v238, s5, 5
	v_writelane_b32 v238, s6, 6
	v_writelane_b32 v238, s7, 7
	v_writelane_b32 v238, s8, 8
	v_writelane_b32 v238, s9, 9
	v_writelane_b32 v238, s10, 10
	v_writelane_b32 v238, s11, 11
	v_writelane_b32 v238, s12, 12
	v_writelane_b32 v238, s13, 13
	v_writelane_b32 v238, s14, 14
	v_writelane_b32 v238, s15, 15
	v_writelane_b32 v238, s16, 16
	v_writelane_b32 v238, s17, 17
	v_writelane_b32 v238, s18, 18
	v_writelane_b32 v238, s19, 19
	v_writelane_b32 v238, s20, 20
	v_writelane_b32 v238, s21, 21
	v_writelane_b32 v238, s22, 22
	v_writelane_b32 v238, s23, 23
	v_writelane_b32 v238, s24, 24
	v_writelane_b32 v238, s25, 25
	v_writelane_b32 v238, s26, 26
	v_writelane_b32 v238, s27, 27
	v_writelane_b32 v238, s28, 28
	v_writelane_b32 v238, s29, 29
	v_writelane_b32 v238, s30, 30
	v_writelane_b32 v238, s31, 31
	v_writelane_b32 v238, s32, 32
	v_writelane_b32 v238, s33, 33
	v_writelane_b32 v238, s34, 34
	v_writelane_b32 v238, s35, 35
	v_writelane_b32 v238, s36, 36
	v_writelane_b32 v238, s37, 37
	v_writelane_b32 v238, s38, 38
	v_writelane_b32 v238, s39, 39
	v_writelane_b32 v238, s40, 40
	v_writelane_b32 v238, s41, 41
	v_writelane_b32 v238, s42, 42
	v_writelane_b32 v238, s43, 43
	v_writelane_b32 v238, s44, 44
	v_writelane_b32 v238, s45, 45
	v_writelane_b32 v238, s46, 46
	v_writelane_b32 v238, s47, 47
	v_writelane_b32 v238, s48, 48
	v_writelane_b32 v238, s49, 49
	v_writelane_b32 v238, s50, 50
	v_writelane_b32 v238, s51, 51
	v_writelane_b32 v238, s52, 52
	v_writelane_b32 v238, s53, 53
	v_writelane_b32 v238, s54, 54
	v_writelane_b32 v238, s55, 55
	v_writelane_b32 v238, s56, 56
	v_writelane_b32 v238, s57, 57
	v_writelane_b32 v238, s58, 58
	v_writelane_b32 v238, s59, 59
	v_writelane_b32 v238, s60, 60
	v_writelane_b32 v238, s61, 61
	v_writelane_b32 v238, s62, 62
	v_writelane_b32 v238, s63, 63
	v_writelane_b32 v239, s64, 0
	v_writelane_b32 v239, s65, 1
	v_writelane_b32 v239, s66, 2
	v_writelane_b32 v239, s67, 3
	v_writelane_b32 v239, s68, 4
	v_writelane_b32 v239, s69, 5
	v_writelane_b32 v239, s70, 6
	v_writelane_b32 v239, s71, 7
	v_writelane_b32 v239, s72, 8
	v_writelane_b32 v239, s73, 9
	v_writelane_b32 v239, s74, 10
	v_writelane_b32 v239, s75, 11
	v_writelane_b32 v239, s76, 12
	v_writelane_b32 v239, s77, 13
	v_writelane_b32 v239, s78, 14
	v_writelane_b32 v239, s79, 15
	v_writelane_b32 v239, s80, 16
	v_writelane_b32 v239, s81, 17
	v_writelane_b32 v239, s82, 18
	v_writelane_b32 v239, s83, 19
	v_writelane_b32 v239, s84, 20
	v_writelane_b32 v239, s85, 21
	v_writelane_b32 v239, s86, 22
	v_writelane_b32 v239, s87, 23
	v_writelane_b32 v239, s88, 24
	v_writelane_b32 v239, s89, 25
	v_writelane_b32 v239, s90, 26
	v_writelane_b32 v239, s91, 27
	v_writelane_b32 v239, s92, 28
	v_writelane_b32 v239, s93, 29
	v_writelane_b32 v239, s94, 30
	v_writelane_b32 v239, s95, 31
	v_writelane_b32 v239, s96, 32
	v_writelane_b32 v239, s97, 33
	v_writelane_b32 v239, s98, 34
	v_writelane_b32 v239, s99, 35
	v_writelane_b32 v239, s100, 36
	v_writelane_b32 v239, s101, 37
	v_writelane_b32 v239, vcc_lo, 38
	v_writelane_b32 v239, vcc_hi, 39
	v_writelane_b32 v239, m0, 40
	s_add_i32 s75, s8, 0xffffff40
	s_mov_b32 s33, 64
	s_lshl_b32 s9, s28, 6
	s_lshl_b32 s4, s75, 3
	s_add_i32 s16, s4, s28
	s_lshl_b32 s18, s33, 3
	s_add_u32 s6, s14, 0x40000
	s_addc_u32 s7, s15, 0
	s_add_u32 s36, s14, 0x400000
	s_addc_u32 s37, s15, 0
	s_add_u32 s34, s14, 0xb400000
	s_addc_u32 s35, s15, 0
	s_load_dwordx2 s[96:97], s[0:1], 0x98
	s_add_u32 s10, s14, 0x10c00000
	s_addc_u32 s11, s15, 0
	s_add_u32 s26, s14, 0x2a800000
	s_addc_u32 s27, s15, 0
	s_waitcnt lgkmcnt(0)
	s_cmp_lt_i32 s96, 1
	s_cselect_b64 s[4:5], -1, 0
	s_cmp_gt_i32 s97, 0
	s_cselect_b64 s[20:21], -1, 0
	s_and_b64 s[4:5], s[4:5], s[20:21]
	s_and_b64 vcc, exec, s[4:5]
	s_mul_i32 s74, s28, 0x4100
	s_cbranch_vccz .Lhb_end
	s_abs_i32 s4, s18
	v_cvt_f32_u32_e32 v0, s4
	s_sub_i32 s5, 0, s4
	s_add_i32 s19, s74, 0
	v_mbcnt_lo_u32_b32 v140, -1, 0
	v_mbcnt_hi_u32_b32 v140, -1, v140
	v_rcp_iflag_f32_e32 v0, v0
	s_nop 0
	v_mul_f32_e32 v0, 0x4f7ffffe, v0
	v_cvt_u32_f32_e32 v0, v0
	s_nop 0
	v_readfirstlane_b32 s17, v0
	s_mul_i32 s5, s5, s17
	s_mul_hi_u32 s5, s17, s5
	s_add_i32 s17, s17, s5
	s_mul_hi_u32 s5, s17, 0x9c4e
	s_mul_i32 s5, s5, s4
	s_sub_i32 s5, 0x9c4e, s5
	s_sub_i32 s17, s5, s4
	s_cmp_ge_u32 s5, s4
	s_cselect_b32 s5, s17, s5
	s_sub_i32 s17, s5, s4
	s_cmp_ge_u32 s5, s4
	s_cselect_b32 s23, s17, s5
	s_sub_i32 s22, 0x9c4e, s23
	s_add_i32 s16, s16, 0x6100
	s_mov_b32 s22, 0x8100
	s_add_u32 s0, s0, 88
	s_addc_u32 s1, s1, 0
	s_add_u32 s34, s14, 0x25000000
	s_addc_u32 s35, s15, 0
	s_cmp_ge_i32 s16, s22
	s_cbranch_scc1 .Lhb_end
	s_cmpk_gt_i32 s16, 0x55ff
	s_cbranch_scc0 .Lhb_14
	s_cmpk_gt_u32 s16, 0x80ff
	s_cbranch_scc0 .Lhb_15
	s_add_u32 s42, s0, 48
	s_addc_u32 s43, s1, 0
	s_add_i32 s17, s16, 0x7f00
	s_and_b32 s20, s17, 0xffff
	s_mul_i32 s20, s20, 0x91a3
	s_load_dwordx2 s[4:5], s[0:1], 0x28
	s_lshr_b32 s20, s20, 23
	s_lshl_b32 s30, s20, 6
	s_mulk_i32 s20, 0xe1
	s_sub_i32 s17, s17, s20
	s_lshl_b32 s17, s17, 6
	s_and_b32 s17, s17, 0xffc0
	s_cbranch_execz .Lhb_16
	s_movk_i32 s25, 0x1040
	s_movk_i32 s24, 0x3820
	s_mov_b64 s[40:41], s[10:11]
	s_branch .Lhb_17

; __device__ __forceinline__ int fresh_lane() { int l; asm volatile("v_mbcnt_lo_u32_b32 %0, -1, 0\n\tv_mbcnt_hi_u32_b32 %0, -1, %0" : "=v"(l)); return l; }
; #define LAS __attribute__((address_space(3)))
; __device__ __forceinline__ unsigned pk2(float lo, float hi) { return pg8::cvt_pk_bf16(lo, hi); }
; __device__ __forceinline__ void xcd_barrier(const XcdBarrier& b) {
;     asm volatile("s_waitcnt vmcnt(0)" ::: "memory");
;     __syncthreads();
;     if (b.w == 0 && fresh_lane() == 0) {
;         unsigned* bar = b.bar;
;         __builtin_amdgcn_s_waitcnt(0);
;         unsigned nloc = b.st[0], nx = b.st[1];
;         if (nloc == 0u) { xcd_barrier_complete(bar, b.x, nloc, nx); b.st[0] = nloc; b.st[1] = nx; }
; __device__ __forceinline__ void p0_finish(bf16* WT, const float* gain, int N, int k0, int n0, int ldw, int blk, int off, int lane, const f32x4 (&v)[16], LAS float* scr) {
;     ...
;     for (int jj = 0; jj < 8; ++jj) { const int n = (lane >> 3) + 8 * jj; const LAS float* s = scr + (8 * c8) * 65 + n;
;         u32x4 o; o.x = pk2(s[0 * 65] * g0[0], s[1 * 65] * g0[1]); o.y = pk2(s[2 * 65] * g0[2], s[3 * 65] * g0[3]); o.z = pk2(s[4 * 65] * g1[0], s[5 * 65] * g1[1]); o.w = pk2(s[6 * 65] * g1[2], s[7 * 65] * g1[3]);
;         const int ng = n0 + n;
;         if (ng < N) { const int row = (ng >> 7) * blk + (ng & 127) + off; __builtin_nontemporal_store(o, (u32x4*)(WT + (size_t)row * ldw + k0 + 8 * c8)); } }
.Lhb_82:
	s_or_b64 exec, exec, s[58:59]
	ds_read2_b32 v[136:137], v149 offset0:56 offset1:121
	s_waitcnt lgkmcnt(0)
	v_mul_f32_e32 v132, v132, v136
	v_mul_f32_e32 v133, v133, v137
	v_cvt_pk_bf16_f32 v132, v132, v133
	ds_read2_b32 v[136:137], v149 offset0:186 offset1:251
	s_waitcnt lgkmcnt(0)
	v_mul_f32_e32 v133, v134, v136
	v_mul_f32_e32 v134, v135, v137
	v_cvt_pk_bf16_f32 v133, v133, v134
	ds_read2_b32 v[134:135], v158 offset0:60 offset1:125
	s_waitcnt lgkmcnt(0)
	v_mul_f32_e32 v128, v128, v134
	v_mul_f32_e32 v129, v129, v135
	v_cvt_pk_bf16_f32 v134, v128, v129
	ds_read2_b32 v[136:137], v158 offset0:190 offset1:255
	v_add_u32_e32 v128, s68, v157
	v_cmp_gt_i32_e32 vcc, s69, v128
	s_waitcnt lgkmcnt(0)
	v_mul_f32_e32 v129, v130, v136
	v_mul_f32_e32 v130, v131, v137
	v_cvt_pk_bf16_f32 v135, v129, v130
	s_and_saveexec_b64 s[58:59], vcc
	s_cbranch_execz .Lhb_21
	v_ashrrev_i32_e32 v129, 7, v128
	v_mul_lo_u32 v129, v129, s20
	v_and_b32_e32 v128, 0x7f, v128
	v_add3_u32 v128, v128, s71, v129
	v_ashrrev_i32_e32 v131, 31, v128
	v_mad_u64_u32 v[128:129], s[60:61], v128, s70, 0
	v_mov_b32_e32 v130, v129
	v_mad_u64_u32 v[130:131], s[60:61], v131, s70, v[130:131]
	v_mov_b32_e32 v129, v130
	v_lshl_add_u64 v[128:129], v[128:129], 1, v[146:147]
	global_store_dwordx4 v[128:129], v[132:135], off nt
	s_branch .Lhb_21
.Lhb_end:
	s_waitcnt vmcnt(0) lgkmcnt(0)
	v_readlane_b32 s2, v239, 40
	s_mov_b32 m0, s2
	v_readlane_b32 s0, v238, 0
	v_readlane_b32 s1, v238, 1
	v_readlane_b32 s2, v238, 2
	v_readlane_b32 s3, v238, 3
	v_readlane_b32 s4, v238, 4
	v_readlane_b32 s5, v238, 5
	v_readlane_b32 s6, v238, 6
	v_readlane_b32 s7, v238, 7
	v_readlane_b32 s8, v238, 8
	v_readlane_b32 s9, v238, 9
	v_readlane_b32 s10, v238, 10
	v_readlane_b32 s11, v238, 11
	v_readlane_b32 s12, v238, 12
	v_readlane_b32 s13, v238, 13
	v_readlane_b32 s14, v238, 14
	v_readlane_b32 s15, v238, 15
	v_readlane_b32 s16, v238, 16
	v_readlane_b32 s17, v238, 17
	v_readlane_b32 s18, v238, 18
	v_readlane_b32 s19, v238, 19
	v_readlane_b32 s20, v238, 20
	v_readlane_b32 s21, v238, 21
	v_readlane_b32 s22, v238, 22
	v_readlane_b32 s23, v238, 23
	v_readlane_b32 s24, v238, 24
	v_readlane_b32 s25, v238, 25
	v_readlane_b32 s26, v238, 26
	v_readlane_b32 s27, v238, 27
	v_readlane_b32 s28, v238, 28
	v_readlane_b32 s29, v238, 29
	v_readlane_b32 s30, v238, 30
	v_readlane_b32 s31, v238, 31
	v_readlane_b32 s32, v238, 32
	v_readlane_b32 s33, v238, 33
	v_readlane_b32 s34, v238, 34
	v_readlane_b32 s35, v238, 35
	v_readlane_b32 s36, v238, 36
	v_readlane_b32 s37, v238, 37
	v_readlane_b32 s38, v238, 38
	v_readlane_b32 s39, v238, 39
	v_readlane_b32 s40, v238, 40
	v_readlane_b32 s41, v238, 41
	v_readlane_b32 s42, v238, 42
	v_readlane_b32 s43, v238, 43
	v_readlane_b32 s44, v238, 44
	v_readlane_b32 s45, v238, 45
	v_readlane_b32 s46, v238, 46
	v_readlane_b32 s47, v238, 47
	v_readlane_b32 s48, v238, 48
	v_readlane_b32 s49, v238, 49
	v_readlane_b32 s50, v238, 50
	v_readlane_b32 s51, v238, 51
	v_readlane_b32 s52, v238, 52
	v_readlane_b32 s53, v238, 53
	v_readlane_b32 s54, v238, 54
	v_readlane_b32 s55, v238, 55
	v_readlane_b32 s56, v238, 56
	v_readlane_b32 s57, v238, 57
	v_readlane_b32 s58, v238, 58
	v_readlane_b32 s59, v238, 59
	v_readlane_b32 s60, v238, 60
	v_readlane_b32 s61, v238, 61
	v_readlane_b32 s62, v238, 62
	v_readlane_b32 s63, v238, 63
	v_readlane_b32 s64, v239, 0
	v_readlane_b32 s65, v239, 1
	v_readlane_b32 s66, v239, 2
	v_readlane_b32 s67, v239, 3
	v_readlane_b32 s68, v239, 4
	v_readlane_b32 s69, v239, 5
	v_readlane_b32 s70, v239, 6
	v_readlane_b32 s71, v239, 7
	v_readlane_b32 s72, v239, 8
	v_readlane_b32 s73, v239, 9
	v_readlane_b32 s74, v239, 10
	v_readlane_b32 s75, v239, 11
	v_readlane_b32 s76, v239, 12
	v_readlane_b32 s77, v239, 13
	v_readlane_b32 s78, v239, 14
	v_readlane_b32 s79, v239, 15
	v_readlane_b32 s80, v239, 16
	v_readlane_b32 s81, v239, 17
	v_readlane_b32 s82, v239, 18
	v_readlane_b32 s83, v239, 19
	v_readlane_b32 s84, v239, 20
	v_readlane_b32 s85, v239, 21
	v_readlane_b32 s86, v239, 22
	v_readlane_b32 s87, v239, 23
	v_readlane_b32 s88, v239, 24
	v_readlane_b32 s89, v239, 25
	v_readlane_b32 s90, v239, 26
	v_readlane_b32 s91, v239, 27
	v_readlane_b32 s92, v239, 28
	v_readlane_b32 s93, v239, 29
	v_readlane_b32 s94, v239, 30
	v_readlane_b32 s95, v239, 31
	v_readlane_b32 s96, v239, 32
	v_readlane_b32 s97, v239, 33
	v_readlane_b32 s98, v239, 34
	v_readlane_b32 s99, v239, 35
	v_readlane_b32 s100, v239, 36
	v_readlane_b32 s101, v239, 37
	v_readlane_b32 vcc_lo, v239, 38
	v_readlane_b32 vcc_hi, v239, 39
.Lhb_done:
	s_cmp_lt_i32 s97, 10
	s_cbranch_scc1 .LBB0_1196
	s_waitcnt vmcnt(0)
	s_cmp_gt_u32 s95, 63
	s_waitcnt lgkmcnt(0)
	s_barrier
	s_cbranch_scc1 .LBB0_1195
	v_mbcnt_lo_u32_b32 v0, -1, 0
	v_mbcnt_hi_u32_b32 v0, -1, v0
	s_nop 0
	v_cmp_eq_u32_e32 vcc, 0, v0
	s_and_saveexec_b64 s[2:3], vcc
	s_cbranch_execz .LBB0_1194
	s_add_i32 s4, 0, 0x27f60
	v_mov_b32_e32 v0, s4
	s_waitcnt vmcnt(0) expcnt(0) lgkmcnt(0)
	ds_read_b32 v2, v0
	s_add_i32 s4, 0, 0x27f64
	v_mov_b32_e32 v0, s4
	ds_read_b32 v0, v0
	s_waitcnt lgkmcnt(1)
	v_cmp_ne_u32_e32 vcc, 0, v2
	s_cbranch_vccnz .LBB0_1158
	v_readlane_b32 s4, v240, 0
	v_readlane_b32 s5, v240, 1
	s_load_dwordx2 s[20:21], s[4:5], 0x4
	s_add_u32 s4, s14, 0x4200
	s_addc_u32 s5, s15, 0
	s_add_u32 s6, s14, 0x4400
	s_addc_u32 s7, s15, 0
	s_add_u32 s34, s14, 0x4500
	s_addc_u32 s35, s15, 0
	s_add_u32 s36, s14, 0x4600
	s_addc_u32 s37, s15, 0
	s_add_u32 s38, s14, 0x4700
	s_addc_u32 s39, s15, 0
	s_add_u32 s40, s14, 0x4800
	s_addc_u32 s41, s15, 0
	s_add_u32 s42, s14, 0x4900
	s_addc_u32 s43, s15, 0
	s_add_u32 s44, s14, 0x4a00
	s_addc_u32 s45, s15, 0
	s_add_u32 s46, s14, 0x4b00
	s_addc_u32 s47, s15, 0
	s_add_u32 s48, s14, 0x4c00
	s_addc_u32 s49, s15, 0
	s_add_u32 s50, s14, 0x4d00
	s_addc_u32 s51, s15, 0
	s_add_u32 s52, s14, 0x4e00
	s_addc_u32 s53, s15, 0
	s_add_u32 s54, s14, 0x4f00
	s_addc_u32 s55, s15, 0
	s_add_u32 s56, s14, 0x5000
	s_addc_u32 s57, s15, 0
	s_add_u32 s58, s14, 0x5100
	s_addc_u32 s59, s15, 0
	s_add_u32 s60, s14, 0x5200
	s_addc_u32 s61, s15, 0
	s_waitcnt lgkmcnt(0)
	s_mul_i32 s9, s20, s33
	s_add_u32 s62, s14, 0x5300
	s_mul_i32 s9, s9, s21
	s_addc_u32 s63, s15, 0
	s_mov_b32 s17, 1
	v_mov_b32_e32 v16, 0
	s_branch .LBB0_1146
